# prep wave: BON store addresses from one base + immediate offsets (42 fewer instructions per chunk)
# speedup vs baseline: 1.0156x; 1.0057x over previous
.LBB0_597:
	s_andn2_b64 vcc, exec, s[36:37]
	s_cbranch_vccnz .LBB0_594
	ds_read2st64_b32 v[236:237], v210 offset1:1
	ds_read2st64_b32 v[238:239], v210 offset0:2 offset1:3
	ds_read2st64_b32 v[240:241], v210 offset0:4 offset1:5
	ds_read2st64_b32 v[242:243], v210 offset0:6 offset1:7
	ds_read2st64_b32 v[244:245], v210 offset0:8 offset1:9
	ds_read2st64_b32 v[246:247], v210 offset0:10 offset1:11
	ds_read2st64_b32 v[248:249], v210 offset0:12 offset1:13
	ds_read2st64_b32 v[250:251], v210 offset0:14 offset1:15
	s_add_i32 s83, s0, 1
	s_cmp_lt_u32 s83, s63
	s_cselect_b32 s0, s83, s0
	s_lshl_b32 s3, s0, 3
	s_sub_i32 s17, s61, s3
	s_and_b64 s[0:1], s[12:13], exec
	s_cselect_b32 s84, s3, s17
	s_add_i32 s3, s84, -1
	s_cmp_lt_u32 s3, s62
	s_cselect_b64 vcc, -1, 0
	s_and_b64 s[0:1], vcc, exec
	s_cselect_b32 s0, s3, s84
	s_add_i32 s0, s0, s14
	v_add_u32_e32 v64, s84, v133
	v_mad_i64_i32 v[100:101], s[0:1], s0, v212, v[96:97]
	v_ashrrev_i32_e32 v65, 31, v64
	s_add_i32 s0, s84, s14
	s_or_b32 s3, s84, 1
	v_lshlrev_b64 v[64:65], 11, v[64:65]
	s_cmp_lt_u32 s3, s62
	v_lshl_add_u64 v[72:73], v[200:201], 0, v[64:65]
	s_cselect_b64 s[36:37], -1, 0
	global_load_dwordx4 v[88:91], v[72:73], off offset:272
	global_load_dwordx4 v[92:95], v[72:73], off offset:256
	global_load_dwordx4 v[68:71], v[72:73], off offset:784
	global_load_dwordx4 v[84:87], v[72:73], off offset:768
	global_load_dwordx4 v[76:79], v[72:73], off offset:400
	global_load_dwordx4 v[80:83], v[72:73], off offset:384
	global_load_dwordx4 v[64:67], v[72:73], off offset:912
	s_nop 0
	global_load_dwordx4 v[72:75], v[72:73], off offset:896
	s_nop 0
	global_load_short_d16_hi v134, v[100:101], off
	global_load_short_d16_hi v135, v[100:101], off offset:128
	global_load_short_d16_hi v136, v[100:101], off offset:256
	v_mad_i64_i32 v[100:101], s[0:1], s0, v212, v[96:97]
	s_and_b64 s[0:1], s[36:37], exec
	s_cselect_b32 s0, s3, s84
	s_add_i32 s0, s0, s14
	s_or_b32 s3, s84, 2
	s_cmp_lt_u32 s3, s62
	s_cselect_b64 s[38:39], -1, 0
	global_load_short_d16_hi v137, v[100:101], off
	global_load_short_d16_hi v138, v[100:101], off offset:128
	global_load_short_d16_hi v139, v[100:101], off offset:256
	v_mad_i64_i32 v[100:101], s[0:1], s0, v212, v[96:97]
	s_and_b64 s[0:1], s[38:39], exec
	s_cselect_b32 s0, s3, s84
	s_add_i32 s0, s0, s14
	s_or_b32 s3, s84, 3
	s_cmp_lt_u32 s3, s62
	s_cselect_b64 s[40:41], -1, 0
	global_load_short_d16_hi v140, v[100:101], off
	global_load_short_d16_hi v141, v[100:101], off offset:128
	global_load_short_d16_hi v142, v[100:101], off offset:256
	v_mad_i64_i32 v[100:101], s[0:1], s0, v212, v[96:97]
	s_and_b64 s[0:1], s[40:41], exec
	s_cselect_b32 s0, s3, s84
	s_add_i32 s0, s0, s14
	s_or_b32 s3, s84, 4
	s_cmp_lt_u32 s3, s62
	s_cselect_b64 s[42:43], -1, 0
	global_load_short_d16_hi v143, v[100:101], off
	global_load_short_d16_hi v144, v[100:101], off offset:128
	global_load_short_d16_hi v145, v[100:101], off offset:256
	v_mad_i64_i32 v[100:101], s[0:1], s0, v212, v[96:97]
	s_and_b64 s[0:1], s[42:43], exec
	s_cselect_b32 s0, s3, s84
	s_add_i32 s0, s0, s14
	s_or_b32 s3, s84, 5
	s_cmp_lt_u32 s3, s62
	s_cselect_b64 s[44:45], -1, 0
	global_load_short_d16_hi v146, v[100:101], off
	global_load_short_d16_hi v147, v[100:101], off offset:128
	global_load_short_d16_hi v148, v[100:101], off offset:256
	v_mad_i64_i32 v[100:101], s[0:1], s0, v212, v[96:97]
	s_and_b64 s[0:1], s[44:45], exec
	s_cselect_b32 s0, s3, s84
	s_add_i32 s0, s0, s14
	s_or_b32 s3, s84, 6
	s_cmp_lt_u32 s3, s62
	s_cselect_b64 s[46:47], -1, 0
	global_load_short_d16_hi v149, v[100:101], off
	global_load_short_d16_hi v150, v[100:101], off offset:128
	global_load_short_d16_hi v151, v[100:101], off offset:256
	v_mad_i64_i32 v[100:101], s[0:1], s0, v212, v[96:97]
	s_and_b64 s[0:1], s[46:47], exec
	s_cselect_b32 s0, s3, s84
	s_add_i32 s0, s0, s14
	s_or_b32 s3, s84, 7
	s_cmp_lt_u32 s3, s62
	s_cselect_b64 s[48:49], -1, 0
	global_load_short_d16_hi v152, v[100:101], off
	global_load_short_d16_hi v153, v[100:101], off offset:128
	global_load_short_d16_hi v154, v[100:101], off offset:256
	v_mad_i64_i32 v[100:101], s[0:1], s0, v212, v[96:97]
	s_and_b64 s[0:1], s[48:49], exec
	s_cselect_b32 s0, s3, s84
	s_add_i32 s0, s0, s14
	s_add_i32 s3, s84, 8
	s_cmp_lt_u32 s3, s62
	s_cselect_b64 s[50:51], -1, 0
	global_load_short_d16_hi v155, v[100:101], off
	global_load_short_d16_hi v156, v[100:101], off offset:128
	global_load_short_d16_hi v157, v[100:101], off offset:256
	v_mad_i64_i32 v[100:101], s[0:1], s0, v212, v[96:97]
	s_and_b64 s[0:1], s[50:51], exec
	s_cselect_b32 s0, s3, s84
	s_add_i32 s0, s0, s14
	global_load_short_d16_hi v158, v[100:101], off
	global_load_short_d16_hi v159, v[100:101], off offset:128
	global_load_short_d16_hi v160, v[100:101], off offset:256
	v_mad_i64_i32 v[100:101], s[0:1], s0, v212, v[96:97]
	global_load_short_d16_hi v161, v[100:101], off
	global_load_short_d16_hi v162, v[100:101], off offset:128
	global_load_short_d16_hi v163, v[100:101], off offset:256
	v_mul_f32_e32 v102, v119, v180
	v_fmac_f32_e32 v102, v118, v178
	v_fmac_f32_e32 v102, v120, v105
	v_mul_f32_e32 v178, v125, v102
	v_mul_f32_e32 v100, v178, v178
	v_mov_b32_e32 v101, v185
	v_mul_f32_e32 v176, v116, v181
	v_fmac_f32_e32 v176, v124, v182
	v_mov_b32_dpp v101, v100 quad_perm:[1,0,3,2] row_mask:0xf bank_mask:0xf
	v_fmac_f32_e32 v101, v178, v178
	v_fmac_f32_e32 v176, v117, v177
	v_mov_b32_e32 v103, v185
	v_add_f32_dpp v100, v101, v101 quad_perm:[2,3,0,1] row_mask:0xf bank_mask:0xf bound_ctrl:1
	s_and_b64 s[0:1], s[12:13], exec
	s_cselect_b32 s21, s15, s74
	v_add_f32_dpp v100, v100, v100 row_half_mirror row_mask:0xf bank_mask:0xf bound_ctrl:1
	s_add_i32 s21, s21, s14
	s_nop 0
	v_add_f32_dpp v100, v100, v100 row_mirror row_mask:0xf bank_mask:0xf bound_ctrl:1
	s_nop 0
	v_readlane_b32 s85, v100, 0
	v_readlane_b32 s20, v100, 16
	v_readlane_b32 s18, v100, 32
	v_readlane_b32 s19, v100, 48
	s_waitcnt lgkmcnt(0)
	v_add_f32_e32 v101, v129, v237
	v_mul_f32_e32 v101, 0xbfb8aa3b, v101
	v_exp_f32_e32 v101, v101
	s_nop 0
	v_add_f32_e32 v101, 1.0, v101
	v_rcp_f32_e32 v183, v101
	s_nop 0
	v_add_f32_e32 v101, -1.0, v183
	v_fma_f32 v101, v126, v101, 1.0
	v_mul_f32_e32 v182, v102, v101
	v_mul_f32_e32 v101, v176, v182
	v_mul_f32_e32 v102, v127, v101
	s_nop 1
	v_mov_b32_dpp v103, v102 quad_perm:[1,0,3,2] row_mask:0xf bank_mask:0xf
	v_fmac_f32_e32 v103, v127, v101
	v_mov_b32_e32 v102, 0
	s_nop 0
	v_add_f32_dpp v101, v103, v103 quad_perm:[2,3,0,1] row_mask:0xf bank_mask:0xf bound_ctrl:1
	s_nop 1
	v_add_f32_dpp v101, v101, v101 row_half_mirror row_mask:0xf bank_mask:0xf bound_ctrl:1
	s_nop 1
	v_mov_b32_dpp v102, v101 row_mirror row_mask:0xf bank_mask:0xf
	s_and_saveexec_b64 s[80:81], s[10:11]
	s_cbranch_execz .LBB0_600
	s_ashr_i32 s1, s21, 31
	s_add_u32 s0, s21, s88
	s_addc_u32 s1, s1, 0
	s_lshl_b64 s[0:1], s[0:1], 9
	v_lshl_add_u64 v[194:195], v[98:99], 0, s[0:1]
	v_add_f32_e32 v101, v101, v102
	global_store_dword v[194:195], v101, off
.LBB0_600:
	s_or_b64 exec, exec, s[80:81]
	s_and_b32 s0, s82, 4
	s_or_b32 s0, s0, s86
	v_mul_f32_e32 v102, v122, v104
	s_mulk_i32 s0, 0x3000
	v_fmac_f32_e32 v102, v121, v179
	v_add_u32_e32 v101, s0, v211
	v_fmac_f32_e32 v102, v123, v106
	ds_write_b32 v101, v102 offset:10240
	v_mul_f32_e32 v179, v116, v177
	v_fmac_f32_e32 v179, v124, v181
	v_mul_f32_e32 v181, v119, v105
	v_fmac_f32_e32 v181, v118, v180
	v_fmac_f32_e32 v181, v120, v107
	v_add_f32_e32 v103, v129, v239
	v_mul_f32_e32 v180, v125, v181
	v_mul_f32_e32 v103, 0xbfb8aa3b, v103
	v_mul_f32_e32 v184, v180, v180
	v_mov_b32_e32 v202, 0
	v_exp_f32_e32 v103, v103
	v_fmac_f32_e32 v179, v117, v175
	v_mov_b32_dpp v202, v184 quad_perm:[1,0,3,2] row_mask:0xf bank_mask:0xf
	v_fmac_f32_e32 v202, v180, v180
	v_add_f32_e32 v103, 1.0, v103
	v_mov_b32_e32 v203, 0
	v_add_f32_dpp v184, v202, v202 quad_perm:[2,3,0,1] row_mask:0xf bank_mask:0xf bound_ctrl:1
	s_nop 1
	v_add_f32_dpp v184, v184, v184 row_half_mirror row_mask:0xf bank_mask:0xf bound_ctrl:1
	s_nop 1
	v_add_f32_dpp v202, v184, v184 row_mirror row_mask:0xf bank_mask:0xf bound_ctrl:1
	v_rcp_f32_e32 v184, v103
	v_readlane_b32 s23, v202, 0
	v_readlane_b32 s25, v202, 16
	v_readlane_b32 s24, v202, 32
	v_add_f32_e32 v103, -1.0, v184
	v_fma_f32 v103, v126, v103, 1.0
	v_mul_f32_e32 v103, v181, v103
	v_mul_f32_e32 v181, v179, v103
	v_readlane_b32 s22, v202, 48
	v_mul_f32_e32 v202, v127, v181
	s_nop 1
	v_mov_b32_dpp v203, v202 quad_perm:[1,0,3,2] row_mask:0xf bank_mask:0xf
	v_fmac_f32_e32 v203, v127, v181
	v_mov_b32_e32 v202, 0
	s_nop 0
	v_add_f32_dpp v181, v203, v203 quad_perm:[2,3,0,1] row_mask:0xf bank_mask:0xf bound_ctrl:1
	s_nop 1
	v_add_f32_dpp v181, v181, v181 row_half_mirror row_mask:0xf bank_mask:0xf bound_ctrl:1
	s_nop 1
	v_mov_b32_dpp v202, v181 row_mirror row_mask:0xf bank_mask:0xf
	s_and_saveexec_b64 s[80:81], s[10:11]
	s_cbranch_execz .LBB0_602
	v_add_f32_e32 v181, v181, v202
	global_store_dword v[194:195], v181, off offset:512
.LBB0_602:
	s_or_b64 exec, exec, s[80:81]
	v_mul_f32_e32 v181, v122, v106
	v_fmac_f32_e32 v181, v121, v104
	v_fmac_f32_e32 v181, v123, v108
	ds_write_b32 v101, v181 offset:10496
	v_mul_f32_e32 v181, v116, v175
	v_fmac_f32_e32 v181, v124, v177
	v_mul_f32_e32 v177, v119, v107
	v_fmac_f32_e32 v177, v118, v105
	v_fmac_f32_e32 v177, v120, v109
	v_mul_f32_e32 v202, v125, v177
	v_mul_f32_e32 v203, v202, v202
	v_mov_b32_e32 v213, 0
	v_add_f32_e32 v105, v129, v241
	v_mul_f32_e32 v105, 0xbfb8aa3b, v105
	v_exp_f32_e32 v105, v105
	v_mov_b32_dpp v213, v203 quad_perm:[1,0,3,2] row_mask:0xf bank_mask:0xf
	v_fmac_f32_e32 v213, v202, v202
	v_fmac_f32_e32 v181, v117, v174
	v_add_f32_e32 v105, 1.0, v105
	v_add_f32_dpp v203, v213, v213 quad_perm:[2,3,0,1] row_mask:0xf bank_mask:0xf bound_ctrl:1
	v_mov_b32_e32 v214, 0
	s_nop 0
	v_add_f32_dpp v203, v203, v203 row_half_mirror row_mask:0xf bank_mask:0xf bound_ctrl:1
	s_nop 1
	v_add_f32_dpp v213, v203, v203 row_mirror row_mask:0xf bank_mask:0xf bound_ctrl:1
	v_rcp_f32_e32 v203, v105
	v_readlane_b32 s26, v213, 0
	v_readlane_b32 s29, v213, 16
	v_readlane_b32 s27, v213, 32
	v_add_f32_e32 v105, -1.0, v203
	v_fma_f32 v105, v126, v105, 1.0
	v_mul_f32_e32 v105, v177, v105
	v_mul_f32_e32 v177, v181, v105
	v_readlane_b32 s28, v213, 48
	v_mul_f32_e32 v213, v127, v177
	s_nop 1
	v_mov_b32_dpp v214, v213 quad_perm:[1,0,3,2] row_mask:0xf bank_mask:0xf
	v_fmac_f32_e32 v214, v127, v177
	v_mov_b32_e32 v213, 0
	s_nop 0
	v_add_f32_dpp v177, v214, v214 quad_perm:[2,3,0,1] row_mask:0xf bank_mask:0xf bound_ctrl:1
	s_nop 1
	v_add_f32_dpp v177, v177, v177 row_half_mirror row_mask:0xf bank_mask:0xf bound_ctrl:1
	s_nop 1
	v_mov_b32_dpp v213, v177 row_mirror row_mask:0xf bank_mask:0xf
	s_and_saveexec_b64 s[80:81], s[10:11]
	s_cbranch_execz .LBB0_604
	v_add_f32_e32 v177, v177, v213
	global_store_dword v[194:195], v177, off offset:1024
.LBB0_604:
	s_or_b64 exec, exec, s[80:81]
	v_mul_f32_e32 v177, v122, v108
	v_fmac_f32_e32 v177, v121, v106
	v_fmac_f32_e32 v177, v123, v110
	ds_write_b32 v101, v177 offset:10752
	v_mul_f32_e32 v177, v116, v174
	v_fmac_f32_e32 v177, v124, v175
	v_mul_f32_e32 v175, v119, v109
	v_fmac_f32_e32 v175, v118, v107
	v_fmac_f32_e32 v175, v120, v111
	v_mul_f32_e32 v213, v125, v175
	v_mul_f32_e32 v214, v213, v213
	v_mov_b32_e32 v215, 0
	v_add_f32_e32 v107, v129, v243
	v_mul_f32_e32 v107, 0xbfb8aa3b, v107
	v_exp_f32_e32 v107, v107
	v_mov_b32_dpp v215, v214 quad_perm:[1,0,3,2] row_mask:0xf bank_mask:0xf
	v_fmac_f32_e32 v215, v213, v213
	v_fmac_f32_e32 v177, v117, v173
	v_add_f32_e32 v107, 1.0, v107
	v_add_f32_dpp v214, v215, v215 quad_perm:[2,3,0,1] row_mask:0xf bank_mask:0xf bound_ctrl:1
	v_mov_b32_e32 v216, 0
	s_nop 0
	v_add_f32_dpp v214, v214, v214 row_half_mirror row_mask:0xf bank_mask:0xf bound_ctrl:1
	s_nop 1
	v_add_f32_dpp v215, v214, v214 row_mirror row_mask:0xf bank_mask:0xf bound_ctrl:1
	v_rcp_f32_e32 v214, v107
	v_readlane_b32 s30, v215, 0
	v_readlane_b32 s35, v215, 16
	v_readlane_b32 s31, v215, 32
	v_add_f32_e32 v107, -1.0, v214
	v_fma_f32 v107, v126, v107, 1.0
	v_mul_f32_e32 v107, v175, v107
	v_mul_f32_e32 v175, v177, v107
	v_readlane_b32 s34, v215, 48
	v_mul_f32_e32 v215, v127, v175
	s_nop 1
	v_mov_b32_dpp v216, v215 quad_perm:[1,0,3,2] row_mask:0xf bank_mask:0xf
	v_fmac_f32_e32 v216, v127, v175
	v_mov_b32_e32 v215, 0
	s_nop 0
	v_add_f32_dpp v175, v216, v216 quad_perm:[2,3,0,1] row_mask:0xf bank_mask:0xf bound_ctrl:1
	s_nop 1
	v_add_f32_dpp v175, v175, v175 row_half_mirror row_mask:0xf bank_mask:0xf bound_ctrl:1
	s_nop 1
	v_mov_b32_dpp v215, v175 row_mirror row_mask:0xf bank_mask:0xf
	s_and_saveexec_b64 s[80:81], s[10:11]
	s_cbranch_execz .LBB0_606
	v_add_f32_e32 v175, v175, v215
	global_store_dword v[194:195], v175, off offset:1536
.LBB0_606:
	s_or_b64 exec, exec, s[80:81]
	v_mul_f32_e32 v175, v122, v110
	v_fmac_f32_e32 v175, v121, v108
	v_fmac_f32_e32 v175, v123, v112
	ds_write_b32 v101, v175 offset:11008
	v_mul_f32_e32 v175, v116, v173
	v_fmac_f32_e32 v175, v124, v174
	v_mul_f32_e32 v174, v119, v111
	v_fmac_f32_e32 v174, v118, v109
	v_fmac_f32_e32 v174, v120, v113
	v_mul_f32_e32 v215, v125, v174
	v_mul_f32_e32 v216, v215, v215
	v_mov_b32_e32 v217, 0
	v_add_f32_e32 v109, v129, v245
	v_mul_f32_e32 v109, 0xbfb8aa3b, v109
	v_exp_f32_e32 v109, v109
	v_mov_b32_dpp v217, v216 quad_perm:[1,0,3,2] row_mask:0xf bank_mask:0xf
	v_fmac_f32_e32 v217, v215, v215
	v_fmac_f32_e32 v175, v117, v172
	v_add_f32_e32 v109, 1.0, v109
	v_add_f32_dpp v216, v217, v217 quad_perm:[2,3,0,1] row_mask:0xf bank_mask:0xf bound_ctrl:1
	v_mov_b32_e32 v218, 0
	s_nop 0
	v_add_f32_dpp v216, v216, v216 row_half_mirror row_mask:0xf bank_mask:0xf bound_ctrl:1
	s_nop 1
	v_add_f32_dpp v217, v216, v216 row_mirror row_mask:0xf bank_mask:0xf bound_ctrl:1
	v_rcp_f32_e32 v216, v109
	v_readlane_b32 s78, v217, 0
	v_readlane_b32 s90, v217, 16
	v_readlane_b32 s79, v217, 32
	v_add_f32_e32 v109, -1.0, v216
	v_fma_f32 v109, v126, v109, 1.0
	v_mul_f32_e32 v109, v174, v109
	v_mul_f32_e32 v174, v175, v109
	v_readlane_b32 s17, v217, 48
	v_mul_f32_e32 v217, v127, v174
	s_nop 1
	v_mov_b32_dpp v218, v217 quad_perm:[1,0,3,2] row_mask:0xf bank_mask:0xf
	v_fmac_f32_e32 v218, v127, v174
	v_mov_b32_e32 v217, 0
	s_nop 0
	v_add_f32_dpp v174, v218, v218 quad_perm:[2,3,0,1] row_mask:0xf bank_mask:0xf bound_ctrl:1
	s_nop 1
	v_add_f32_dpp v174, v174, v174 row_half_mirror row_mask:0xf bank_mask:0xf bound_ctrl:1
	s_nop 1
	v_mov_b32_dpp v217, v174 row_mirror row_mask:0xf bank_mask:0xf
	s_and_saveexec_b64 s[80:81], s[10:11]
	s_cbranch_execz .LBB0_608
	v_add_f32_e32 v174, v174, v217
	global_store_dword v[194:195], v174, off offset:2048
.LBB0_608:
	s_or_b64 exec, exec, s[80:81]
	v_mul_f32_e32 v174, v122, v112
	v_fmac_f32_e32 v174, v121, v110
	v_fmac_f32_e32 v174, v123, v114
	ds_write_b32 v101, v174 offset:11264
	v_mul_f32_e32 v174, v116, v172
	v_fmac_f32_e32 v174, v124, v173
	v_mul_f32_e32 v173, v119, v113
	v_fmac_f32_e32 v173, v118, v111
	v_fmac_f32_e32 v173, v120, v115
	v_mul_f32_e32 v217, v125, v173
	v_mul_f32_e32 v218, v217, v217
	v_mov_b32_e32 v219, 0
	v_add_f32_e32 v111, v129, v247
	v_mul_f32_e32 v111, 0xbfb8aa3b, v111
	v_exp_f32_e32 v111, v111
	v_mov_b32_dpp v219, v218 quad_perm:[1,0,3,2] row_mask:0xf bank_mask:0xf
	v_fmac_f32_e32 v219, v217, v217
	v_fmac_f32_e32 v174, v117, v167
	v_add_f32_e32 v111, 1.0, v111
	v_add_f32_dpp v218, v219, v219 quad_perm:[2,3,0,1] row_mask:0xf bank_mask:0xf bound_ctrl:1
	v_mov_b32_e32 v220, 0
	s_nop 0
	v_add_f32_dpp v218, v218, v218 row_half_mirror row_mask:0xf bank_mask:0xf bound_ctrl:1
	s_nop 1
	v_add_f32_dpp v219, v218, v218 row_mirror row_mask:0xf bank_mask:0xf bound_ctrl:1
	v_rcp_f32_e32 v218, v111
	v_readlane_b32 s1, v219, 0
	v_readlane_b32 s92, v219, 16
	v_readlane_b32 s0, v219, 32
	v_add_f32_e32 v111, -1.0, v218
	v_fma_f32 v111, v126, v111, 1.0
	v_mul_f32_e32 v111, v173, v111
	v_mul_f32_e32 v173, v174, v111
	v_readlane_b32 s91, v219, 48
	v_mul_f32_e32 v219, v127, v173
	s_nop 1
	v_mov_b32_dpp v220, v219 quad_perm:[1,0,3,2] row_mask:0xf bank_mask:0xf
	v_fmac_f32_e32 v220, v127, v173
	v_mov_b32_e32 v219, 0
	s_nop 0
	v_add_f32_dpp v173, v220, v220 quad_perm:[2,3,0,1] row_mask:0xf bank_mask:0xf bound_ctrl:1
	s_nop 1
	v_add_f32_dpp v173, v173, v173 row_half_mirror row_mask:0xf bank_mask:0xf bound_ctrl:1
	s_nop 1
	v_mov_b32_dpp v219, v173 row_mirror row_mask:0xf bank_mask:0xf
	s_and_saveexec_b64 s[80:81], s[10:11]
	s_cbranch_execz .LBB0_610
	v_add_f32_e32 v173, v173, v219
	global_store_dword v[194:195], v173, off offset:2560
.LBB0_610:
	s_or_b64 exec, exec, s[80:81]
	v_mul_f32_e32 v173, v122, v114
	v_mul_f32_e32 v220, v119, v115
	v_fmac_f32_e32 v173, v121, v112
	v_fmac_f32_e32 v220, v118, v113
	v_fmac_f32_e32 v173, v123, v164
	ds_write_b32 v101, v173 offset:11520
	v_mul_f32_e32 v173, v116, v167
	v_fmac_f32_e32 v220, v120, v168
	v_add_f32_e32 v113, v129, v249
	v_fmac_f32_e32 v173, v124, v172
	v_mul_f32_e32 v172, v125, v220
	v_mul_f32_e32 v113, 0xbfb8aa3b, v113
	v_mul_f32_e32 v219, v172, v172
	v_mov_b32_e32 v221, 0
	v_exp_f32_e32 v113, v113
	v_fmac_f32_e32 v173, v117, v169
	v_mov_b32_dpp v221, v219 quad_perm:[1,0,3,2] row_mask:0xf bank_mask:0xf
	v_fmac_f32_e32 v221, v172, v172
	v_add_f32_e32 v113, 1.0, v113
	v_mov_b32_e32 v222, 0
	v_add_f32_dpp v219, v221, v221 quad_perm:[2,3,0,1] row_mask:0xf bank_mask:0xf bound_ctrl:1
	s_nop 1
	v_add_f32_dpp v219, v219, v219 row_half_mirror row_mask:0xf bank_mask:0xf bound_ctrl:1
	s_nop 1
	v_add_f32_dpp v221, v219, v219 row_mirror row_mask:0xf bank_mask:0xf bound_ctrl:1
	v_rcp_f32_e32 v219, v113
	v_readlane_b32 s94, v221, 0
	v_readlane_b32 s97, v221, 16
	v_readlane_b32 s95, v221, 32
	v_add_f32_e32 v113, -1.0, v219
	v_fma_f32 v113, v126, v113, 1.0
	v_mul_f32_e32 v113, v220, v113
	v_mul_f32_e32 v220, v173, v113
	v_readlane_b32 s96, v221, 48
	v_mul_f32_e32 v221, v127, v220
	s_nop 1
	v_mov_b32_dpp v222, v221 quad_perm:[1,0,3,2] row_mask:0xf bank_mask:0xf
	v_fmac_f32_e32 v222, v127, v220
	v_mov_b32_e32 v221, 0
	s_nop 0
	v_add_f32_dpp v220, v222, v222 quad_perm:[2,3,0,1] row_mask:0xf bank_mask:0xf bound_ctrl:1
	s_nop 1
	v_add_f32_dpp v220, v220, v220 row_half_mirror row_mask:0xf bank_mask:0xf bound_ctrl:1
	s_nop 1
	v_mov_b32_dpp v221, v220 row_mirror row_mask:0xf bank_mask:0xf
	s_and_saveexec_b64 s[80:81], s[10:11]
	s_cbranch_execz .LBB0_612
	v_add_f32_e32 v222, v220, v221
	global_store_dword v[194:195], v222, off offset:3072
.LBB0_612:
	s_or_b64 exec, exec, s[80:81]
	v_mul_f32_e32 v169, v116, v169
	v_fmac_f32_e32 v169, v124, v167
	v_mul_f32_e32 v220, v122, v164
	v_fmac_f32_e32 v169, v117, v171
	v_mul_f32_e32 v171, v119, v168
	v_fmac_f32_e32 v220, v121, v114
	v_fmac_f32_e32 v171, v118, v115
	v_fmac_f32_e32 v171, v120, v170
	v_mul_f32_e32 v168, v125, v171
	v_mul_f32_e32 v167, v168, v168
	v_mov_b32_e32 v170, 0
	v_add_f32_e32 v115, v129, v251
	v_mul_f32_e32 v115, 0xbfb8aa3b, v115
	v_exp_f32_e32 v115, v115
	v_mov_b32_dpp v170, v167 quad_perm:[1,0,3,2] row_mask:0xf bank_mask:0xf
	v_fmac_f32_e32 v170, v168, v168
	v_fmac_f32_e32 v220, v123, v166
	v_add_f32_e32 v115, 1.0, v115
	v_add_f32_dpp v167, v170, v170 quad_perm:[2,3,0,1] row_mask:0xf bank_mask:0xf bound_ctrl:1
	ds_write_b32 v101, v220 offset:11776
	v_mov_b32_e32 v220, 0
	v_add_f32_dpp v167, v167, v167 row_half_mirror row_mask:0xf bank_mask:0xf bound_ctrl:1
	s_nop 1
	v_add_f32_dpp v170, v167, v167 row_mirror row_mask:0xf bank_mask:0xf bound_ctrl:1
	v_rcp_f32_e32 v167, v115
	v_readlane_b32 s3, v170, 0
	v_readlane_b32 s64, v170, 16
	v_readlane_b32 s52, v170, 32
	v_add_f32_e32 v115, -1.0, v167
	v_fma_f32 v115, v126, v115, 1.0
	v_mul_f32_e32 v115, v171, v115
	v_readlane_b32 s53, v170, 48
	v_mul_f32_e32 v170, v169, v115
	v_mul_f32_e32 v171, v127, v170
	s_nop 1
	v_mov_b32_dpp v220, v171 quad_perm:[1,0,3,2] row_mask:0xf bank_mask:0xf
	v_fmac_f32_e32 v220, v127, v170
	v_mov_b32_e32 v171, 0
	s_nop 0
	v_add_f32_dpp v170, v220, v220 quad_perm:[2,3,0,1] row_mask:0xf bank_mask:0xf bound_ctrl:1
	s_nop 1
	v_add_f32_dpp v170, v170, v170 row_half_mirror row_mask:0xf bank_mask:0xf bound_ctrl:1
	s_nop 1
	v_mov_b32_dpp v171, v170 row_mirror row_mask:0xf bank_mask:0xf
	s_and_saveexec_b64 s[80:81], s[10:11]
	s_cbranch_execz .LBB0_614
	v_add_f32_e32 v220, v170, v171
	global_store_dword v[194:195], v220, off offset:3584
